# attention C/B row-max: 53-op canonicalising max tree replaced by a 16-op v_max3 tree (same result on non-NaN values)
# baseline (speedup 1.0000x reference)
; #define FLAS __attribute__((address_space(3)))
; #define FA_SB() __builtin_amdgcn_sched_barrier(0)
; template <int MODE> __device__ __forceinline__ void attn_unit(FLAS unsigned char* lds, const Unit u) {
;     ...
;         if (MODE == 2) active = (k0 + 63 >= q0w - 1024) && (k0 <= q0w + 31 + 1024);
;         if (active) {
;             f32x16 p0, p1;
;             bf16x8 kf[8];
;             { const FLAS unsigned char* kb = lds + L_K + cur * KBUF;
; #pragma unroll
;               for (int d0 = 0; d0 < 4; ++d0) { const int ko = (2 * d0 + hi) * 1024 + ((r32 ^ (2 * d0 + hi)) * 16); kf[2 * d0] = *(const FLAS bf16x8*)(kb + ko); kf[2 * d0 + 1] = *(const FLAS bf16x8*)(kb + ko + 512); } }
;             float cb = 0.f; bool zinit = false;
;             if (MODE == 0) { const int dmin = k0 - (q0w + 31), dmax = k0 + 63 - q0w;
;                 if (dmin >= 559) { cb = L[LUT_C + 600]; zinit = true; } else if (dmax <= -559) { cb = L[LUT_C - 600]; zinit = true; } }
;             if (zinit) {
;                 const f32x16 z16 = {0.f,0.f,0.f,0.f,0.f,0.f,0.f,0.f,0.f,0.f,0.f,0.f,0.f,0.f,0.f,0.f};
;                 FA_SB();
;                 p0 = __builtin_amdgcn_mfma_f32_32x32x16_bf16(kf[0], qr[0], z16, 0, 0, 0); p1 = __builtin_amdgcn_mfma_f32_32x32x16_bf16(kf[1], qr[0], z16, 0, 0, 0);
; #pragma unroll
;                 for (int d0 = 1; d0 < 4; ++d0) { p0 = __builtin_amdgcn_mfma_f32_32x32x16_bf16(kf[2 * d0], qr[d0], p0, 0, 0, 0); p1 = __builtin_amdgcn_mfma_f32_32x32x16_bf16(kf[2 * d0 + 1], qr[d0], p1, 0, 0, 0); }
;             } else {
;                 if (MODE == 0 || MODE == 2) { const FLAS float* lp = L + (k0 - q + LUT_C + 4 * hi);
; #pragma unroll
;                     for (int r = 0; r < 16; ++r) { p0[r] = lp[(r & 3) + 8 * (r >> 2)]; p1[r] = lp[32 + (r & 3) + 8 * (r >> 2)]; }
;                 } else { const FLAS float* lp = L + ((t - gi + 7) * 128 + 63 - qc + 4 * hi);
; #pragma unroll
;                     for (int r = 0; r < 16; ++r) { const int kc = (r & 3) + 8 * (r >> 2) + 4 * hi;
;                         const float v0 = lp[(r & 3) + 8 * (r >> 2)], v1 = lp[32 + (r & 3) + 8 * (r >> 2)];
;                         p0[r] = ((unsigned)(kc - cstart) < 16u) ? v0 : NEG; p1[r] = ((unsigned)(kc + 32 - cstart) < 16u) ? v1 : NEG; } }
;                 FA_SB();
; #pragma unroll
.LBB0_498:
	s_and_b32 s24, s8, 1
	s_add_i32 s9, s22, 63
	s_cmp_ge_i32 s9, s12
	s_cselect_b64 s[34:35], -1, 0
	s_cmp_le_i32 s22, s21
	s_cselect_b64 s[38:39], -1, 0
	s_and_b64 s[34:35], s[34:35], s[38:39]
	s_andn2_b64 vcc, exec, s[34:35]
	s_cbranch_vccnz .LBB0_506
	s_lshl_b32 s9, s24, 13
	s_add_i32 s9, s9, 0
	v_add3_u32 v32, s9, v139, v140
	ds_read_b128 v[88:91], v32
	ds_read_b128 v[92:95], v32 offset:512
	v_add3_u32 v32, s9, v141, v142
	ds_read_b128 v[102:105], v32
	ds_read_b128 v[106:109], v32 offset:512
	v_add3_u32 v32, s9, v143, v144
	ds_read_b128 v[110:113], v32
	ds_read_b128 v[114:117], v32 offset:512
	v_add3_u32 v32, s9, v145, v146
	ds_read_b128 v[118:121], v32
	ds_read_b128 v[122:125], v32 offset:512
	ds_read2_b32 v[32:33], v147 offset1:1
	ds_read2_b32 v[34:35], v147 offset0:2 offset1:3
	ds_read2_b32 v[36:37], v147 offset0:8 offset1:9
	ds_read2_b32 v[38:39], v147 offset0:10 offset1:11
	ds_read2_b32 v[48:49], v147 offset0:32 offset1:33
	ds_read2_b32 v[50:51], v147 offset0:34 offset1:35
	ds_read2_b32 v[52:53], v147 offset0:40 offset1:41
	ds_read2_b32 v[54:55], v147 offset0:42 offset1:43
	ds_read2_b32 v[40:41], v147 offset0:16 offset1:17
	ds_read2_b32 v[42:43], v147 offset0:18 offset1:19
	ds_read2_b32 v[44:45], v147 offset0:24 offset1:25
	ds_read2_b32 v[46:47], v147 offset0:26 offset1:27
	ds_read2_b32 v[56:57], v147 offset0:48 offset1:49
	ds_read2_b32 v[58:59], v147 offset0:50 offset1:51
	ds_read2_b32 v[60:61], v147 offset0:56 offset1:57
	ds_read2_b32 v[62:63], v147 offset0:58 offset1:59
	s_xor_b64 s[6:7], s[6:7], -1
	s_waitcnt lgkmcnt(4)
	v_mfma_f32_32x32x16_bf16 v[32:47], v[88:91], v[64:67], v[32:47]
	s_mul_i32 s9, s24, 0x4800
	v_add_u32_e32 v149, s9, v138
	s_waitcnt lgkmcnt(0)
	v_mfma_f32_32x32x16_bf16 v[48:63], v[92:95], v[64:67], v[48:63]
	ds_read_b128 v[92:95], v149 offset:16384
	ds_read_b128 v[88:91], v149 offset:20992
	v_mfma_f32_32x32x16_bf16 v[32:47], v[102:105], v[68:71], v[32:47]
	v_mfma_f32_32x32x16_bf16 v[48:63], v[106:109], v[68:71], v[48:63]
	v_mfma_f32_32x32x16_bf16 v[32:47], v[110:113], v[72:75], v[32:47]
	v_mfma_f32_32x32x16_bf16 v[48:63], v[114:117], v[72:75], v[48:63]
	v_mfma_f32_32x32x16_bf16 v[32:47], v[118:121], v[76:79], v[32:47]
	v_mfma_f32_32x32x16_bf16 v[48:63], v[122:125], v[76:79], v[48:63]
	s_and_b32 s8, s8, 3
	s_cmp_lg_u32 s8, 0
	s_cselect_b64 s[8:9], -1, 0
	v_sub_f32_e32 v102, 0, v148
	s_and_b64 s[8:9], s[6:7], s[8:9]
	s_nop 5
	v_add_f32_e32 v132, v102, v32
	v_add_f32_e32 v133, v102, v33
	v_add_f32_e32 v120, v102, v48
	v_add_f32_e32 v121, v102, v49
	v_add_f32_e32 v130, v102, v34
	v_add_f32_e32 v131, v102, v35
	v_add_f32_e32 v116, v102, v50
	v_add_f32_e32 v117, v102, v51
	v_add_f32_e32 v128, v102, v36
	v_add_f32_e32 v129, v102, v37
	v_add_f32_e32 v114, v102, v52
	v_add_f32_e32 v115, v102, v53
	v_add_f32_e32 v126, v102, v38
	v_add_f32_e32 v127, v102, v39
	v_add_f32_e32 v110, v102, v54
	v_add_f32_e32 v111, v102, v55
	v_add_f32_e32 v124, v102, v40
	v_add_f32_e32 v125, v102, v41
	v_add_f32_e32 v108, v102, v56
	v_add_f32_e32 v109, v102, v57
	v_add_f32_e32 v122, v102, v42
	v_add_f32_e32 v123, v102, v43
	v_add_f32_e32 v106, v102, v58
	v_add_f32_e32 v107, v102, v59
	v_add_f32_e32 v118, v102, v44
	v_add_f32_e32 v119, v102, v45
	v_add_f32_e32 v104, v102, v60
	v_add_f32_e32 v105, v102, v61
	v_add_f32_e32 v112, v102, v46
	v_add_f32_e32 v113, v102, v47
	v_add_f32_e32 v103, v102, v63
	v_add_f32_e32 v102, v102, v62
	s_and_b64 vcc, exec, s[8:9]
	s_mov_b32 s25, 0x41000000
	s_cbranch_vccnz .LBB0_507
	v_max3_f32 v32, v121, v133, v116
	v_max3_f32 v33, v130, v117, v131
	v_max3_f32 v32, v32, v132, v120
	v_max3_f32 v33, v33, v114, v128
	v_max3_f32 v32, v32, v115, v129
	v_max3_f32 v33, v33, v110, v126
	v_max3_f32 v32, v32, v111, v127
	v_max3_f32 v33, v33, v108, v124
	v_max3_f32 v32, v32, v109, v125
	v_max3_f32 v33, v33, v106, v122
	v_max3_f32 v32, v32, v107, v123
	v_max3_f32 v33, v33, v104, v118
	v_max3_f32 v32, v32, v105, v119
	v_max3_f32 v33, v33, v102, v112
	v_max3_f32 v32, v32, v103, v113
	v_max_f32_e32 v32, v32, v33
	v_mov_b32_e32 v33, v32
	s_nop 1
	v_permlane32_swap_b32 v32, v33
	s_nop 1
	s_mov_b64 s[8:9], -1
	v_max_f32_e32 v164, v32, v33
	s_and_b64 vcc, exec, s[6:7]
	s_movk_i32 s38, 0x87f
	s_mov_b64 s[34:35], 0x800
	s_cbranch_vccz .LBB0_503
	v_cmp_lt_f32_e32 vcc, s25, v164
	s_cbranch_vccz .LBB0_508
	v_max_f32_e32 v32, v164, v164
	v_max_f32_e32 v167, 0, v32
	v_exp_f32_e64 v184, -v167
	v_add_f32_e32 v148, v148, v167
	v_sub_f32_e32 v166, v132, v167
	v_sub_f32_e32 v165, v133, v167
	v_pk_mul_f32 v[62:63], v[30:31], v[184:185] op_sel_hi:[1,0]
	v_pk_mul_f32 v[60:61], v[28:29], v[184:185] op_sel_hi:[1,0]
	v_pk_mul_f32 v[58:59], v[26:27], v[184:185] op_sel_hi:[1,0]
	v_pk_mul_f32 v[56:57], v[24:25], v[184:185] op_sel_hi:[1,0]
	v_pk_mul_f32 v[54:55], v[22:23], v[184:185] op_sel_hi:[1,0]
	v_pk_mul_f32 v[52:53], v[20:21], v[184:185] op_sel_hi:[1,0]
	v_pk_mul_f32 v[50:51], v[18:19], v[184:185] op_sel_hi:[1,0]
	v_pk_mul_f32 v[48:49], v[16:17], v[184:185] op_sel_hi:[1,0]
	v_pk_mul_f32 v[46:47], v[14:15], v[184:185] op_sel_hi:[1,0]
	v_pk_mul_f32 v[44:45], v[12:13], v[184:185] op_sel_hi:[1,0]
	v_pk_mul_f32 v[42:43], v[10:11], v[184:185] op_sel_hi:[1,0]
	v_pk_mul_f32 v[40:41], v[8:9], v[184:185] op_sel_hi:[1,0]
	v_pk_mul_f32 v[38:39], v[6:7], v[184:185] op_sel_hi:[1,0]
	v_pk_mul_f32 v[36:37], v[4:5], v[184:185] op_sel_hi:[1,0]
	v_pk_mul_f32 v[34:35], v[2:3], v[184:185] op_sel_hi:[1,0]
	v_pk_mul_f32 v[32:33], v[0:1], v[184:185] op_sel_hi:[1,0]
	v_sub_f32_e32 v163, v130, v167
	v_sub_f32_e32 v162, v131, v167
	v_sub_f32_e32 v161, v128, v167
	v_sub_f32_e32 v160, v129, v167
	v_sub_f32_e32 v159, v126, v167
	v_sub_f32_e32 v158, v127, v167
	v_sub_f32_e32 v157, v124, v167
	v_sub_f32_e32 v156, v125, v167
	v_sub_f32_e32 v155, v122, v167
	v_sub_f32_e32 v154, v123, v167
	v_sub_f32_e32 v153, v118, v167
	v_sub_f32_e32 v152, v119, v167
	v_sub_f32_e32 v151, v112, v167
	v_sub_f32_e32 v150, v113, v167
	v_sub_f32_e32 v182, v120, v167
	v_sub_f32_e32 v181, v121, v167
	v_sub_f32_e32 v180, v116, v167
	v_sub_f32_e32 v179, v117, v167
	v_sub_f32_e32 v178, v114, v167
	v_sub_f32_e32 v177, v115, v167
	v_sub_f32_e32 v176, v110, v167
	v_sub_f32_e32 v175, v111, v167
	v_sub_f32_e32 v174, v108, v167
	v_sub_f32_e32 v173, v109, v167
	v_sub_f32_e32 v172, v106, v167
	v_sub_f32_e32 v171, v107, v167
	v_sub_f32_e32 v170, v104, v167
	v_sub_f32_e32 v169, v105, v167
	v_sub_f32_e32 v168, v102, v167
	v_sub_f32_e32 v167, v103, v167
	v_mul_f32_e32 v183, v137, v184
	s_mov_b64 s[8:9], 0

; #define FLAS __attribute__((address_space(3)))
; #define FA_SB() __builtin_amdgcn_sched_barrier(0)
; template <int MODE> __device__ __forceinline__ void attn_unit(FLAS unsigned char* lds, const Unit u) {
;     ...
;         if (MODE == 1) active = (t >= rstart) && (t < rstart + 8);
;         if (MODE == 2) active = (k0 + 63 >= q0w - 1024) && (k0 <= q0w + 31 + 1024);
;         if (active) {
;             f32x16 p0, p1;
;             bf16x8 kf[8];
;             { const FLAS unsigned char* kb = lds + L_K + cur * KBUF;
; #pragma unroll
;               for (int d0 = 0; d0 < 4; ++d0) { const int ko = (2 * d0 + hi) * 1024 + ((r32 ^ (2 * d0 + hi)) * 16); kf[2 * d0] = *(const FLAS bf16x8*)(kb + ko); kf[2 * d0 + 1] = *(const FLAS bf16x8*)(kb + ko + 512); } }
;             float cb = 0.f; bool zinit = false;
;             if (MODE == 0) { const int dmin = k0 - (q0w + 31), dmax = k0 + 63 - q0w;
;                 if (dmin >= 559) { cb = L[LUT_C + 600]; zinit = true; } else if (dmax <= -559) { cb = L[LUT_C - 600]; zinit = true; } }
;             if (zinit) {
;                 const f32x16 z16 = {0.f,0.f,0.f,0.f,0.f,0.f,0.f,0.f,0.f,0.f,0.f,0.f,0.f,0.f,0.f,0.f};
;                 FA_SB();
;                 p0 = __builtin_amdgcn_mfma_f32_32x32x16_bf16(kf[0], qr[0], z16, 0, 0, 0); p1 = __builtin_amdgcn_mfma_f32_32x32x16_bf16(kf[1], qr[0], z16, 0, 0, 0);
; #pragma unroll
;                 for (int d0 = 1; d0 < 4; ++d0) { p0 = __builtin_amdgcn_mfma_f32_32x32x16_bf16(kf[2 * d0], qr[d0], p0, 0, 0, 0); p1 = __builtin_amdgcn_mfma_f32_32x32x16_bf16(kf[2 * d0 + 1], qr[d0], p1, 0, 0, 0); }
;             } else {
;                 if (MODE == 0 || MODE == 2) { const FLAS float* lp = L + (k0 - q + LUT_C + 4 * hi);
; #pragma unroll
;                     for (int r = 0; r < 16; ++r) { p0[r] = lp[(r & 3) + 8 * (r >> 2)]; p1[r] = lp[32 + (r & 3) + 8 * (r >> 2)]; }
;                 } else { const FLAS float* lp = L + ((t - gi + 7) * 128 + 63 - qc + 4 * hi);
; #pragma unroll
;                     for (int r = 0; r < 16; ++r) { const int kc = (r & 3) + 8 * (r >> 2) + 4 * hi;
;                         const float v0 = lp[(r & 3) + 8 * (r >> 2)], v1 = lp[32 + (r & 3) + 8 * (r >> 2)];
;                         p0[r] = ((unsigned)(kc - cstart) < 16u) ? v0 : NEG; p1[r] = ((unsigned)(kc + 32 - cstart) < 16u) ? v1 : NEG; } }
;                 FA_SB();
; #pragma unroll
.LBB0_530:
	s_and_b32 s21, s14, 1
	s_cmp_ge_i32 s14, s26
	s_cselect_b64 vcc, -1, 0
	s_cmp_lt_i32 s14, s12
	s_cselect_b64 s[28:29], -1, 0
	s_and_b64 s[28:29], vcc, s[28:29]
	s_andn2_b64 vcc, exec, s[28:29]
	s_cbranch_vccnz .LBB0_539
	s_lshl_b32 s15, s21, 13
	s_add_i32 s15, s15, 0
	v_add3_u32 v32, s15, v138, v139
	ds_read_b128 v[88:91], v32
	ds_read_b128 v[92:95], v32 offset:512
	v_add3_u32 v32, s15, v140, v141
	ds_read_b128 v[102:105], v32
	ds_read_b128 v[106:109], v32 offset:512
	v_add3_u32 v32, s15, v142, v143
	ds_read_b128 v[110:113], v32
	ds_read_b128 v[114:117], v32 offset:512
	v_add3_u32 v32, s15, v144, v145
	ds_read_b128 v[118:121], v32
	ds_read_b128 v[122:125], v32 offset:512
	ds_read2_b32 v[32:33], v147 offset1:1
	ds_read2_b32 v[34:35], v147 offset0:2 offset1:3
	ds_read2_b32 v[36:37], v147 offset0:8 offset1:9
	ds_read2_b32 v[38:39], v147 offset0:10 offset1:11
	ds_read2_b32 v[48:49], v147 offset0:32 offset1:33
	ds_read2_b32 v[50:51], v147 offset0:34 offset1:35
	ds_read2_b32 v[52:53], v147 offset0:40 offset1:41
	ds_read2_b32 v[54:55], v147 offset0:42 offset1:43
	ds_read2_b32 v[40:41], v147 offset0:16 offset1:17
	ds_read2_b32 v[42:43], v147 offset0:18 offset1:19
	ds_read2_b32 v[44:45], v147 offset0:24 offset1:25
	ds_read2_b32 v[46:47], v147 offset0:26 offset1:27
	ds_read2_b32 v[56:57], v147 offset0:48 offset1:49
	ds_read2_b32 v[58:59], v147 offset0:50 offset1:51
	ds_read2_b32 v[60:61], v147 offset0:56 offset1:57
	ds_read2_b32 v[62:63], v147 offset0:58 offset1:59
	s_xor_b64 s[22:23], s[22:23], -1
	s_waitcnt lgkmcnt(14)
	v_cndmask_b32_e64 v34, v242, v34, s[66:67]
	v_cndmask_b32_e64 v33, v242, v33, s[68:69]
	v_cndmask_b32_e64 v32, v242, v32, s[70:71]
	v_cndmask_b32_e64 v35, v242, v35, s[64:65]
	s_waitcnt lgkmcnt(13)
	v_cndmask_b32_e64 v36, v242, v36, s[62:63]
	v_cndmask_b32_e64 v37, v242, v37, s[60:61]
	s_waitcnt lgkmcnt(12)
	v_cndmask_b32_e64 v38, v242, v38, s[58:59]
	v_cndmask_b32_e64 v39, v242, v39, s[56:57]
	s_waitcnt lgkmcnt(7)
	v_cndmask_b32_e64 v40, v242, v40, s[54:55]
	v_cndmask_b32_e64 v41, v242, v41, s[52:53]
	s_waitcnt lgkmcnt(6)
	v_cndmask_b32_e64 v42, v242, v42, s[50:51]
	v_cndmask_b32_e64 v43, v242, v43, s[48:49]
	s_waitcnt lgkmcnt(5)
	v_cndmask_b32_e64 v44, v242, v44, s[46:47]
	v_cndmask_b32_e64 v45, v242, v45, s[44:45]
	s_waitcnt lgkmcnt(4)
	v_cndmask_b32_e64 v46, v242, v46, s[42:43]
	v_cndmask_b32_e64 v47, v242, v47, s[40:41]
	v_cndmask_b32_e64 v50, v242, v50, s[4:5]
	v_cndmask_b32_e64 v49, v242, v49, s[6:7]
	v_cndmask_b32_e64 v48, v242, v48, s[8:9]
	v_cndmask_b32_e64 v51, v242, v51, s[96:97]
	v_cndmask_b32_e64 v52, v242, v52, s[94:95]
	v_cndmask_b32_e64 v53, v242, v53, s[92:93]
	v_cndmask_b32_e64 v54, v242, v54, s[90:91]
	v_cndmask_b32_e64 v55, v242, v55, s[88:89]
	s_waitcnt lgkmcnt(3)
	v_cndmask_b32_e64 v56, v242, v56, s[86:87]
	v_cndmask_b32_e64 v57, v242, v57, s[84:85]
	s_waitcnt lgkmcnt(2)
	v_cndmask_b32_e64 v58, v242, v58, s[82:83]
	v_cndmask_b32_e64 v59, v242, v59, s[80:81]
	s_waitcnt lgkmcnt(1)
	v_cndmask_b32_e64 v60, v242, v60, s[78:79]
	v_cndmask_b32_e64 v61, v242, v61, s[76:77]
	s_waitcnt lgkmcnt(0)
	v_cndmask_b32_e64 v62, v242, v62, s[74:75]
	v_cndmask_b32_e64 v63, v242, v63, s[72:73]
	v_mfma_f32_32x32x16_bf16 v[32:47], v[88:91], v[64:67], v[32:47]
	s_mul_i32 s15, s21, 0x4800
	v_add_u32_e32 v149, s15, v137
	v_mfma_f32_32x32x16_bf16 v[48:63], v[92:95], v[64:67], v[48:63]
	ds_read_b128 v[92:95], v149 offset:16384
	ds_read_b128 v[88:91], v149 offset:20992
	v_mfma_f32_32x32x16_bf16 v[32:47], v[102:105], v[68:71], v[32:47]
	v_mfma_f32_32x32x16_bf16 v[48:63], v[106:109], v[68:71], v[48:63]
	v_mfma_f32_32x32x16_bf16 v[32:47], v[110:113], v[72:75], v[32:47]
	v_mfma_f32_32x32x16_bf16 v[48:63], v[114:117], v[72:75], v[48:63]
	v_mfma_f32_32x32x16_bf16 v[32:47], v[118:121], v[76:79], v[32:47]
	v_mfma_f32_32x32x16_bf16 v[48:63], v[122:125], v[76:79], v[48:63]
	s_and_b32 s14, s14, 3
	s_cmp_lg_u32 s14, 0
	s_cselect_b64 s[14:15], -1, 0
	v_sub_f32_e32 v102, 0, v148
	s_and_b64 s[14:15], s[22:23], s[14:15]
	s_nop 5
	v_add_f32_e32 v132, v102, v32
	v_add_f32_e32 v133, v102, v33
	v_add_f32_e32 v120, v102, v48
	v_add_f32_e32 v121, v102, v49
	v_add_f32_e32 v130, v102, v34
	v_add_f32_e32 v131, v102, v35
	v_add_f32_e32 v116, v102, v50
	v_add_f32_e32 v117, v102, v51
	v_add_f32_e32 v128, v102, v36
	v_add_f32_e32 v129, v102, v37
	v_add_f32_e32 v114, v102, v52
	v_add_f32_e32 v115, v102, v53
	v_add_f32_e32 v126, v102, v38
	v_add_f32_e32 v127, v102, v39
	v_add_f32_e32 v110, v102, v54
	v_add_f32_e32 v111, v102, v55
	v_add_f32_e32 v124, v102, v40
	v_add_f32_e32 v125, v102, v41
	v_add_f32_e32 v108, v102, v56
	v_add_f32_e32 v109, v102, v57
	v_add_f32_e32 v122, v102, v42
	v_add_f32_e32 v123, v102, v43
	v_add_f32_e32 v106, v102, v58
	v_add_f32_e32 v107, v102, v59
	v_add_f32_e32 v118, v102, v44
	v_add_f32_e32 v119, v102, v45
	v_add_f32_e32 v104, v102, v60
	v_add_f32_e32 v105, v102, v61
	v_add_f32_e32 v112, v102, v46
	v_add_f32_e32 v113, v102, v47
	v_add_f32_e32 v103, v102, v63
	v_add_f32_e32 v102, v102, v62
	s_and_b64 vcc, exec, s[14:15]
	s_cbranch_vccnz .LBB0_538
; __device__ __forceinline__ float xhalf_max(float m) { unsigned a = __builtin_bit_cast(unsigned, m), b = a; xswap(a, b); return __builtin_fmaxf(__builtin_bit_cast(float, a), __builtin_bit_cast(float, b)); }
; template <int MODE> __device__ __forceinline__ void attn_unit(FLAS unsigned char* lds, const Unit u) {
;     ...
;             float rm = __builtin_fmaxf(p0[0], p1[0]);
; #pragma unroll
;             for (int r = 1; r < 16; ++r) rm = __builtin_fmaxf(rm, __builtin_fmaxf(p0[r], p1[r]));
;             rm = xhalf_max(rm);
;             if (first) {
;                 const float dl = __builtin_fmaxf(rm, -1000.0f); mrun = dl;
; #pragma unroll
;                 for (int r = 0; r < 16; ++r) { p0[r] = p0[r] - dl; p1[r] = p1[r] - dl; }
;                 first = false;
;             } else if (__any(rm > 8.0f)) { const float dl = __builtin_fmaxf(rm, 0.0f); const float f = __builtin_amdgcn_exp2f(-dl); mrun += dl; lsum *= f;
; #pragma unroll
;                 for (int i = 0; i < NDB; ++i) o[i] = o[i] * f;
; #pragma unroll
;                 for (int r = 0; r < 16; ++r) { p0[r] = p0[r] - dl; p1[r] = p1[r] - dl; } }
	v_max3_f32 v32, v121, v133, v116
	v_max3_f32 v33, v130, v117, v131
	v_max3_f32 v32, v32, v132, v120
	v_max3_f32 v33, v33, v114, v128
	v_max3_f32 v32, v32, v115, v129
	v_max3_f32 v33, v33, v110, v126
	v_max3_f32 v32, v32, v111, v127
	v_max3_f32 v33, v33, v108, v124
	v_max3_f32 v32, v32, v109, v125
	v_max3_f32 v33, v33, v106, v122
	v_max3_f32 v32, v32, v107, v123
	v_max3_f32 v33, v33, v104, v118
	v_max3_f32 v32, v32, v105, v119
	v_max3_f32 v33, v33, v102, v112
	v_max3_f32 v32, v32, v103, v113
	v_max_f32_e32 v32, v32, v33
	v_mov_b32_e32 v33, v32
	s_nop 1
	v_permlane32_swap_b32 v33, v32
	s_nop 1
	s_mov_b64 s[14:15], -1
	v_max_f32_e32 v163, v33, v32
	s_and_b64 vcc, exec, s[22:23]
	s_cbranch_vccz .LBB0_535
	s_mov_b32 s14, 0x41000000
	v_cmp_lt_f32_e32 vcc, s14, v163
	s_cbranch_vccz .LBB0_538
	v_max_f32_e32 v32, v163, v163
	v_max_f32_e32 v167, 0, v32
	v_exp_f32_e64 v184, -v167
	v_add_f32_e32 v148, v148, v167
	v_sub_f32_e32 v166, v132, v167
	v_sub_f32_e32 v165, v133, v167
	v_pk_mul_f32 v[62:63], v[30:31], v[184:185] op_sel_hi:[1,0]
	v_pk_mul_f32 v[60:61], v[28:29], v[184:185] op_sel_hi:[1,0]
	v_pk_mul_f32 v[58:59], v[26:27], v[184:185] op_sel_hi:[1,0]
	v_pk_mul_f32 v[56:57], v[24:25], v[184:185] op_sel_hi:[1,0]
	v_pk_mul_f32 v[54:55], v[22:23], v[184:185] op_sel_hi:[1,0]
	v_pk_mul_f32 v[52:53], v[20:21], v[184:185] op_sel_hi:[1,0]
	v_pk_mul_f32 v[50:51], v[18:19], v[184:185] op_sel_hi:[1,0]
	v_pk_mul_f32 v[48:49], v[16:17], v[184:185] op_sel_hi:[1,0]
	v_pk_mul_f32 v[46:47], v[14:15], v[184:185] op_sel_hi:[1,0]
	v_pk_mul_f32 v[44:45], v[12:13], v[184:185] op_sel_hi:[1,0]
	v_pk_mul_f32 v[42:43], v[10:11], v[184:185] op_sel_hi:[1,0]
	v_pk_mul_f32 v[40:41], v[8:9], v[184:185] op_sel_hi:[1,0]
	v_pk_mul_f32 v[38:39], v[6:7], v[184:185] op_sel_hi:[1,0]
	v_pk_mul_f32 v[36:37], v[4:5], v[184:185] op_sel_hi:[1,0]
	v_pk_mul_f32 v[34:35], v[2:3], v[184:185] op_sel_hi:[1,0]
	v_pk_mul_f32 v[32:33], v[0:1], v[184:185] op_sel_hi:[1,0]
	v_sub_f32_e32 v164, v130, v167
	v_sub_f32_e32 v162, v131, v167
	v_sub_f32_e32 v161, v128, v167
	v_sub_f32_e32 v160, v129, v167
	v_sub_f32_e32 v159, v126, v167
	v_sub_f32_e32 v158, v127, v167
	v_sub_f32_e32 v157, v124, v167
	v_sub_f32_e32 v156, v125, v167
	v_sub_f32_e32 v155, v122, v167
	v_sub_f32_e32 v154, v123, v167
	v_sub_f32_e32 v153, v118, v167
	v_sub_f32_e32 v152, v119, v167
	v_sub_f32_e32 v151, v112, v167
	v_sub_f32_e32 v150, v113, v167
	v_sub_f32_e32 v182, v120, v167
	v_sub_f32_e32 v181, v121, v167
	v_sub_f32_e32 v180, v116, v167
	v_sub_f32_e32 v179, v117, v167
	v_sub_f32_e32 v178, v114, v167
	v_sub_f32_e32 v177, v115, v167
	v_sub_f32_e32 v176, v110, v167
	v_sub_f32_e32 v175, v111, v167
	v_sub_f32_e32 v174, v108, v167
	v_sub_f32_e32 v173, v109, v167
	v_sub_f32_e32 v172, v106, v167
	v_sub_f32_e32 v171, v107, v167
	v_sub_f32_e32 v170, v104, v167
	v_sub_f32_e32 v169, v105, v167
	v_sub_f32_e32 v168, v102, v167
	v_sub_f32_e32 v167, v103, v167
	v_mul_f32_e32 v183, v146, v184
	s_mov_b64 s[14:15], 0
